# fnpipe + xnpipe (pipelined XN conversion rows in P0) on top of v83
# baseline (speedup 1.0000x reference)
; __device__ __forceinline__ unsigned cvt_pk_bf16(float lo, float hi) { unsigned r; asm volatile("v_cvt_pk_bf16_f32 %0, %1, %2" : "=v"(r) : "v"(lo), "v"(hi)); return r; }
; __device__ __forceinline__ void p0_prologue(const Params& p, LAS unsigned char* lds, int vcu_in, int G_in, int cu0, int part) {
;     ...
;         f32x4 g[8];
; #pragma unroll
;         for (int j = 0; j < 8; ++j) g[j] = ((const f32x4*)p.norm_in)[lane + 64 * j];
;         bf16_t* XN = (bf16_t*)(ws + WS_XN);
;         for (int row = gw; row < T_TOK; row += NGW) {
;             const float* xr = row < 16384 ? p.x_prompt + (size_t)row * 2048 : p.x_sample + (size_t)(row - 16384) * 2048;
;             f32x4 v[8]; float s = 0.f;
; #pragma unroll
;             for (int j = 0; j < 8; ++j) { v[j] = ((const f32x4*)xr)[lane + 64 * j]; s += (v[j][0] * v[j][0] + v[j][1] * v[j][1]) + (v[j][2] * v[j][2] + v[j][3] * v[j][3]); }
;             s = wave_sum(s, lane);
;             if (lane == 0) SS0[row] = s;
;             u32x2* o = (u32x2*)(XN + (size_t)row * 2048);
; #pragma unroll
;             for (int j = 0; j < 8; ++j) { const f32x4 y = v[j] * g[j]; u32x2 w; w.x = cvt_pk_bf16(y[0], y[1]); w.y = cvt_pk_bf16(y[2], y[3]); o[lane + 64 * j] = w; }
;         }
.Lp0_xn_entry:
	s_mov_b32 s0, 0x8000
	s_mov_b64 s[6:7], exec
	v_readfirstlane_b32 s8, v66
	s_mov_b32 s16, 0
	s_brev_b32 s17, 1
	s_cmp_lt_i32 s8, s0
	s_cbranch_scc0 .LBB0_281
	v_lshlrev_b32_e32 v100, 4, v128
	v_lshlrev_b32_e32 v98, 3, v128
	v_mov_b32_e32 v97, 0
	v_add_u32_e32 v99, 0x1000, v100
	global_load_dwordx4 v[0:3], v100, s[60:61] offset:0
	global_load_dwordx4 v[4:7], v100, s[60:61] offset:1024
	global_load_dwordx4 v[8:11], v100, s[60:61] offset:2048
	global_load_dwordx4 v[12:15], v100, s[60:61] offset:3072
	global_load_dwordx4 v[16:19], v99, s[60:61] offset:0
	global_load_dwordx4 v[20:23], v99, s[60:61] offset:1024
	global_load_dwordx4 v[24:27], v99, s[60:61] offset:2048
	global_load_dwordx4 v[28:31], v99, s[60:61] offset:3072
	s_cmp_lt_i32 s8, 0x4000
	s_cselect_b32 s10, s52, s54
	s_cselect_b32 s11, s53, s55
	s_and_b32 s5, s8, 0x3fff
	s_lshl_b32 s5, s5, 13
	s_add_u32 s10, s10, s5
	s_addc_u32 s11, s11, 0
	global_load_dwordx4 v[32:35], v100, s[10:11] offset:0
	global_load_dwordx4 v[36:39], v100, s[10:11] offset:1024
	global_load_dwordx4 v[40:43], v100, s[10:11] offset:2048
	global_load_dwordx4 v[44:47], v100, s[10:11] offset:3072
	global_load_dwordx4 v[48:51], v99, s[10:11] offset:0
	global_load_dwordx4 v[52:55], v99, s[10:11] offset:1024
	global_load_dwordx4 v[56:59], v99, s[10:11] offset:2048
	global_load_dwordx4 v[60:63], v99, s[10:11] offset:3072
	s_mov_b32 s1, 1
.Lxn_half_A:
	s_add_i32 s9, s8, s4
	s_cmp_lt_i32 s9, s0
	s_cbranch_scc0 .Lxn_A_last
	s_cmp_lt_i32 s9, 0x4000
	s_cselect_b32 s10, s52, s54
	s_cselect_b32 s11, s53, s55
	s_and_b32 s5, s9, 0x3fff
	s_lshl_b32 s5, s5, 13
	s_add_u32 s10, s10, s5
	s_addc_u32 s11, s11, 0
	global_load_dwordx4 v[102:105], v100, s[10:11] offset:0
	global_load_dwordx4 v[106:109], v100, s[10:11] offset:1024
	global_load_dwordx4 v[110:113], v100, s[10:11] offset:2048
	global_load_dwordx4 v[114:117], v100, s[10:11] offset:3072
	global_load_dwordx4 v[118:121], v99, s[10:11] offset:0
	global_load_dwordx4 v[122:125], v99, s[10:11] offset:1024
	global_load_dwordx4 v[70:73], v99, s[10:11] offset:2048
	global_load_dwordx4 v[74:77], v99, s[10:11] offset:3072
	s_cmp_eq_u32 s1, 0
	s_cbranch_scc1 .Lxn_A_w17
	s_mov_b32 s1, 0
	s_waitcnt vmcnt(8)
	s_branch .Lxn_A_go
.Lxn_A_w17:
	s_waitcnt vmcnt(17)
	s_branch .Lxn_A_go

; __device__ __forceinline__ unsigned cvt_pk_bf16(float lo, float hi) { unsigned r; asm volatile("v_cvt_pk_bf16_f32 %0, %1, %2" : "=v"(r) : "v"(lo), "v"(hi)); return r; }
; __device__ __forceinline__ void p0_prologue(const Params& p, LAS unsigned char* lds, int vcu_in, int G_in, int cu0, int part) {
;     ...
;         for (int row = gw; row < T_TOK; row += NGW) {
;             const float* xr = row < 16384 ? p.x_prompt + (size_t)row * 2048 : p.x_sample + (size_t)(row - 16384) * 2048;
;             f32x4 v[8]; float s = 0.f;
; #pragma unroll
;             for (int j = 0; j < 8; ++j) { v[j] = ((const f32x4*)xr)[lane + 64 * j]; s += (v[j][0] * v[j][0] + v[j][1] * v[j][1]) + (v[j][2] * v[j][2] + v[j][3] * v[j][3]); }
;             s = wave_sum(s, lane);
;             if (lane == 0) SS0[row] = s;
;             u32x2* o = (u32x2*)(XN + (size_t)row * 2048);
; #pragma unroll
;             for (int j = 0; j < 8; ++j) { const f32x4 y = v[j] * g[j]; u32x2 w; w.x = cvt_pk_bf16(y[0], y[1]); w.y = cvt_pk_bf16(y[2], y[3]); o[lane + 64 * j] = w; }
;         }
.Lxn_A_go:
	s_lshl_b32 s5, s8, 12
	s_add_u32 s12, s68, s5
	s_addc_u32 s13, s69, 0
	s_add_u32 s12, s12, 0x14000000
	s_addc_u32 s13, s13, 0
	s_lshl_b32 s5, s8, 2
	s_add_u32 s14, s68, s5
	s_addc_u32 s15, s69, 0
	s_add_u32 s14, s14, 0x1ed00000
	s_addc_u32 s15, s15, 0
	v_pk_mul_f32 v[78:79], v[32:33], v[32:33]
	v_pk_mul_f32 v[80:81], v[34:35], v[34:35]
	v_pk_fma_f32 v[78:79], v[36:37], v[36:37], v[78:79]
	v_pk_fma_f32 v[80:81], v[38:39], v[38:39], v[80:81]
	v_pk_fma_f32 v[78:79], v[40:41], v[40:41], v[78:79]
	v_pk_fma_f32 v[80:81], v[42:43], v[42:43], v[80:81]
	v_pk_fma_f32 v[78:79], v[44:45], v[44:45], v[78:79]
	v_pk_fma_f32 v[80:81], v[46:47], v[46:47], v[80:81]
	v_pk_fma_f32 v[78:79], v[48:49], v[48:49], v[78:79]
	v_pk_fma_f32 v[80:81], v[50:51], v[50:51], v[80:81]
	v_pk_fma_f32 v[78:79], v[52:53], v[52:53], v[78:79]
	v_pk_fma_f32 v[80:81], v[54:55], v[54:55], v[80:81]
	v_pk_fma_f32 v[78:79], v[56:57], v[56:57], v[78:79]
	v_pk_fma_f32 v[80:81], v[58:59], v[58:59], v[80:81]
	v_pk_fma_f32 v[78:79], v[60:61], v[60:61], v[78:79]
	v_pk_fma_f32 v[80:81], v[62:63], v[62:63], v[80:81]
	v_pk_add_f32 v[78:79], v[78:79], v[80:81]
	s_nop 0
	v_add_f32_e32 v82, v78, v79
	v_pk_mul_f32 v[32:33], v[32:33], v[0:1]
	v_pk_mul_f32 v[34:35], v[34:35], v[2:3]
	v_add_f32_dpp v82, v82, v82 quad_perm:[1,0,3,2] row_mask:0xf bank_mask:0xf
	v_pk_mul_f32 v[36:37], v[36:37], v[4:5]
	v_pk_mul_f32 v[38:39], v[38:39], v[6:7]
	v_add_f32_dpp v82, v82, v82 quad_perm:[2,3,0,1] row_mask:0xf bank_mask:0xf
	v_pk_mul_f32 v[40:41], v[40:41], v[8:9]
	v_pk_mul_f32 v[42:43], v[42:43], v[10:11]
	v_add_f32_dpp v82, v82, v82 row_half_mirror row_mask:0xf bank_mask:0xf
	v_pk_mul_f32 v[44:45], v[44:45], v[12:13]
	v_pk_mul_f32 v[46:47], v[46:47], v[14:15]
	v_add_f32_dpp v82, v82, v82 row_mirror row_mask:0xf bank_mask:0xf
	v_pk_mul_f32 v[48:49], v[48:49], v[16:17]
	v_pk_mul_f32 v[50:51], v[50:51], v[18:19]
	v_add_f32_dpp v82, v82, v82 row_bcast:15 row_mask:0xa bank_mask:0xf
	v_pk_mul_f32 v[52:53], v[52:53], v[20:21]
	v_pk_mul_f32 v[54:55], v[54:55], v[22:23]
	v_add_f32_dpp v82, v82, v82 row_bcast:31 row_mask:0xc bank_mask:0xf
	v_pk_mul_f32 v[56:57], v[56:57], v[24:25]
	v_pk_mul_f32 v[58:59], v[58:59], v[26:27]
	v_pk_mul_f32 v[60:61], v[60:61], v[28:29]
	v_pk_mul_f32 v[62:63], v[62:63], v[30:31]
	s_mov_b64 exec, s[16:17]
	global_store_dword v97, v82, s[14:15]
	s_mov_b64 exec, s[6:7]
	v_cvt_pk_bf16_f32 v32, v32, v33
	v_cvt_pk_bf16_f32 v33, v34, v35
	global_store_dwordx2 v98, v[32:33], s[12:13] offset:0
	v_cvt_pk_bf16_f32 v36, v36, v37
	v_cvt_pk_bf16_f32 v37, v38, v39
	global_store_dwordx2 v98, v[36:37], s[12:13] offset:512
	v_cvt_pk_bf16_f32 v40, v40, v41
	v_cvt_pk_bf16_f32 v41, v42, v43
	global_store_dwordx2 v98, v[40:41], s[12:13] offset:1024
	v_cvt_pk_bf16_f32 v44, v44, v45
	v_cvt_pk_bf16_f32 v45, v46, v47
	global_store_dwordx2 v98, v[44:45], s[12:13] offset:1536
	v_cvt_pk_bf16_f32 v48, v48, v49
	v_cvt_pk_bf16_f32 v49, v50, v51
	global_store_dwordx2 v98, v[48:49], s[12:13] offset:2048
	v_cvt_pk_bf16_f32 v52, v52, v53
	v_cvt_pk_bf16_f32 v53, v54, v55
	global_store_dwordx2 v98, v[52:53], s[12:13] offset:2560
	v_cvt_pk_bf16_f32 v56, v56, v57
	v_cvt_pk_bf16_f32 v57, v58, v59
	global_store_dwordx2 v98, v[56:57], s[12:13] offset:3072
	v_cvt_pk_bf16_f32 v60, v60, v61
	v_cvt_pk_bf16_f32 v61, v62, v63
	global_store_dwordx2 v98, v[60:61], s[12:13] offset:3584
	s_mov_b32 s8, s9
	s_cmp_lt_i32 s8, s0
	s_cbranch_scc0 .LBB0_281
.Lxn_half_B:
	s_add_i32 s9, s8, s4
	s_cmp_lt_i32 s9, s0
	s_cbranch_scc0 .Lxn_B_last
	s_cmp_lt_i32 s9, 0x4000
	s_cselect_b32 s10, s52, s54
	s_cselect_b32 s11, s53, s55
	s_and_b32 s5, s9, 0x3fff
	s_lshl_b32 s5, s5, 13
	s_add_u32 s10, s10, s5
	s_addc_u32 s11, s11, 0
	global_load_dwordx4 v[32:35], v100, s[10:11] offset:0
	global_load_dwordx4 v[36:39], v100, s[10:11] offset:1024
	global_load_dwordx4 v[40:43], v100, s[10:11] offset:2048
	global_load_dwordx4 v[44:47], v100, s[10:11] offset:3072
	global_load_dwordx4 v[48:51], v99, s[10:11] offset:0
	global_load_dwordx4 v[52:55], v99, s[10:11] offset:1024
	global_load_dwordx4 v[56:59], v99, s[10:11] offset:2048
	global_load_dwordx4 v[60:63], v99, s[10:11] offset:3072
	s_waitcnt vmcnt(17)
	s_branch .Lxn_B_go

; __device__ __forceinline__ unsigned cvt_pk_bf16(float lo, float hi) { unsigned r; asm volatile("v_cvt_pk_bf16_f32 %0, %1, %2" : "=v"(r) : "v"(lo), "v"(hi)); return r; }
; __device__ __forceinline__ void p0_prologue(const Params& p, LAS unsigned char* lds, int vcu_in, int G_in, int cu0, int part) {
;     ...
;         for (int row = gw; row < T_TOK; row += NGW) {
;             const float* xr = row < 16384 ? p.x_prompt + (size_t)row * 2048 : p.x_sample + (size_t)(row - 16384) * 2048;
;             f32x4 v[8]; float s = 0.f;
; #pragma unroll
;             for (int j = 0; j < 8; ++j) { v[j] = ((const f32x4*)xr)[lane + 64 * j]; s += (v[j][0] * v[j][0] + v[j][1] * v[j][1]) + (v[j][2] * v[j][2] + v[j][3] * v[j][3]); }
;             s = wave_sum(s, lane);
;             if (lane == 0) SS0[row] = s;
;             u32x2* o = (u32x2*)(XN + (size_t)row * 2048);
; #pragma unroll
;             for (int j = 0; j < 8; ++j) { const f32x4 y = v[j] * g[j]; u32x2 w; w.x = cvt_pk_bf16(y[0], y[1]); w.y = cvt_pk_bf16(y[2], y[3]); o[lane + 64 * j] = w; }
;         }
.Lxn_B_go:
	s_lshl_b32 s5, s8, 12
	s_add_u32 s12, s68, s5
	s_addc_u32 s13, s69, 0
	s_add_u32 s12, s12, 0x14000000
	s_addc_u32 s13, s13, 0
	s_lshl_b32 s5, s8, 2
	s_add_u32 s14, s68, s5
	s_addc_u32 s15, s69, 0
	s_add_u32 s14, s14, 0x1ed00000
	s_addc_u32 s15, s15, 0
	v_pk_mul_f32 v[78:79], v[102:103], v[102:103]
	v_pk_mul_f32 v[80:81], v[104:105], v[104:105]
	v_pk_fma_f32 v[78:79], v[106:107], v[106:107], v[78:79]
	v_pk_fma_f32 v[80:81], v[108:109], v[108:109], v[80:81]
	v_pk_fma_f32 v[78:79], v[110:111], v[110:111], v[78:79]
	v_pk_fma_f32 v[80:81], v[112:113], v[112:113], v[80:81]
	v_pk_fma_f32 v[78:79], v[114:115], v[114:115], v[78:79]
	v_pk_fma_f32 v[80:81], v[116:117], v[116:117], v[80:81]
	v_pk_fma_f32 v[78:79], v[118:119], v[118:119], v[78:79]
	v_pk_fma_f32 v[80:81], v[120:121], v[120:121], v[80:81]
	v_pk_fma_f32 v[78:79], v[122:123], v[122:123], v[78:79]
	v_pk_fma_f32 v[80:81], v[124:125], v[124:125], v[80:81]
	v_pk_fma_f32 v[78:79], v[70:71], v[70:71], v[78:79]
	v_pk_fma_f32 v[80:81], v[72:73], v[72:73], v[80:81]
	v_pk_fma_f32 v[78:79], v[74:75], v[74:75], v[78:79]
	v_pk_fma_f32 v[80:81], v[76:77], v[76:77], v[80:81]
	v_pk_add_f32 v[78:79], v[78:79], v[80:81]
	s_nop 0
	v_add_f32_e32 v82, v78, v79
	v_pk_mul_f32 v[102:103], v[102:103], v[0:1]
	v_pk_mul_f32 v[104:105], v[104:105], v[2:3]
	v_add_f32_dpp v82, v82, v82 quad_perm:[1,0,3,2] row_mask:0xf bank_mask:0xf
	v_pk_mul_f32 v[106:107], v[106:107], v[4:5]
	v_pk_mul_f32 v[108:109], v[108:109], v[6:7]
	v_add_f32_dpp v82, v82, v82 quad_perm:[2,3,0,1] row_mask:0xf bank_mask:0xf
	v_pk_mul_f32 v[110:111], v[110:111], v[8:9]
	v_pk_mul_f32 v[112:113], v[112:113], v[10:11]
	v_add_f32_dpp v82, v82, v82 row_half_mirror row_mask:0xf bank_mask:0xf
	v_pk_mul_f32 v[114:115], v[114:115], v[12:13]
	v_pk_mul_f32 v[116:117], v[116:117], v[14:15]
	v_add_f32_dpp v82, v82, v82 row_mirror row_mask:0xf bank_mask:0xf
	v_pk_mul_f32 v[118:119], v[118:119], v[16:17]
	v_pk_mul_f32 v[120:121], v[120:121], v[18:19]
	v_add_f32_dpp v82, v82, v82 row_bcast:15 row_mask:0xa bank_mask:0xf
	v_pk_mul_f32 v[122:123], v[122:123], v[20:21]
	v_pk_mul_f32 v[124:125], v[124:125], v[22:23]
	v_add_f32_dpp v82, v82, v82 row_bcast:31 row_mask:0xc bank_mask:0xf
	v_pk_mul_f32 v[70:71], v[70:71], v[24:25]
	v_pk_mul_f32 v[72:73], v[72:73], v[26:27]
	v_pk_mul_f32 v[74:75], v[74:75], v[28:29]
	v_pk_mul_f32 v[76:77], v[76:77], v[30:31]
	s_mov_b64 exec, s[16:17]
	global_store_dword v97, v82, s[14:15]
	s_mov_b64 exec, s[6:7]
	v_cvt_pk_bf16_f32 v102, v102, v103
	v_cvt_pk_bf16_f32 v103, v104, v105
	global_store_dwordx2 v98, v[102:103], s[12:13] offset:0
	v_cvt_pk_bf16_f32 v106, v106, v107
	v_cvt_pk_bf16_f32 v107, v108, v109
	global_store_dwordx2 v98, v[106:107], s[12:13] offset:512
	v_cvt_pk_bf16_f32 v110, v110, v111
	v_cvt_pk_bf16_f32 v111, v112, v113
	global_store_dwordx2 v98, v[110:111], s[12:13] offset:1024
	v_cvt_pk_bf16_f32 v114, v114, v115
	v_cvt_pk_bf16_f32 v115, v116, v117
	global_store_dwordx2 v98, v[114:115], s[12:13] offset:1536
	v_cvt_pk_bf16_f32 v118, v118, v119
	v_cvt_pk_bf16_f32 v119, v120, v121
	global_store_dwordx2 v98, v[118:119], s[12:13] offset:2048
	v_cvt_pk_bf16_f32 v122, v122, v123
	v_cvt_pk_bf16_f32 v123, v124, v125
	global_store_dwordx2 v98, v[122:123], s[12:13] offset:2560
	v_cvt_pk_bf16_f32 v70, v70, v71
	v_cvt_pk_bf16_f32 v71, v72, v73
	global_store_dwordx2 v98, v[70:71], s[12:13] offset:3072
	v_cvt_pk_bf16_f32 v74, v74, v75
	v_cvt_pk_bf16_f32 v75, v76, v77
	global_store_dwordx2 v98, v[74:75], s[12:13] offset:3584
	s_mov_b32 s8, s9
	s_cmp_lt_i32 s8, s0
	s_cbranch_scc0 .LBB0_281
	s_branch .Lxn_half_A
